# sample (split-K) units of the four output projections: partial tiles stored to dead workspace with agent-scope write-through stores, per-tile arrival counter, each unit reduces 1/16 of the tile in fix
# speedup vs baseline: 1.0338x; 1.0338x over previous
.Lop0_orig:
	s_sub_i32 s0, s21, 0x100
	s_lshl_b32 s0, s0, 17
	s_lshl_b32 s1, s14, 15
	s_add_i32 s0, s0, s1
	s_add_u32 s0, s0, 0xe219000
	v_lshl_add_u32 v130, v166, 4, v167
	v_lshlrev_b32_e32 v130, 4, v130
	v_add_u32_e32 v131, s0, v130
	s_cmp_lg_u32 s15, 0
	s_cbranch_scc1 .Lsr0_nost
	global_store_dwordx4 v131, v[126:129], s[84:85] offset:0 sc1
	global_store_dwordx4 v131, v[122:125], s[84:85] offset:1024 sc1
	global_store_dwordx4 v131, v[118:121], s[84:85] offset:2048 sc1
	global_store_dwordx4 v131, v[114:117], s[84:85] offset:3072 sc1
	v_add_u32_e32 v131, 0x1000, v131
	global_store_dwordx4 v131, v[110:113], s[84:85] offset:0 sc1
	global_store_dwordx4 v131, v[106:109], s[84:85] offset:1024 sc1
	global_store_dwordx4 v131, v[102:105], s[84:85] offset:2048 sc1
	global_store_dwordx4 v131, v[98:101], s[84:85] offset:3072 sc1
	v_add_u32_e32 v131, 0x1000, v131
	global_store_dwordx4 v131, v[94:97], s[84:85] offset:0 sc1
	global_store_dwordx4 v131, v[90:93], s[84:85] offset:1024 sc1
	global_store_dwordx4 v131, v[86:89], s[84:85] offset:2048 sc1
	global_store_dwordx4 v131, v[82:85], s[84:85] offset:3072 sc1
	v_add_u32_e32 v131, 0x1000, v131
	global_store_dwordx4 v131, v[78:81], s[84:85] offset:0 sc1
	global_store_dwordx4 v131, v[74:77], s[84:85] offset:1024 sc1
	global_store_dwordx4 v131, v[70:73], s[84:85] offset:2048 sc1
	global_store_dwordx4 v131, v[66:69], s[84:85] offset:3072 sc1
	v_add_u32_e32 v131, 0x1000, v131
	global_store_dwordx4 v131, v[62:65], s[84:85] offset:0 sc1
	global_store_dwordx4 v131, v[58:61], s[84:85] offset:1024 sc1
	global_store_dwordx4 v131, v[54:57], s[84:85] offset:2048 sc1
	global_store_dwordx4 v131, v[50:53], s[84:85] offset:3072 sc1
	v_add_u32_e32 v131, 0x1000, v131
	global_store_dwordx4 v131, v[46:49], s[84:85] offset:0 sc1
	global_store_dwordx4 v131, v[42:45], s[84:85] offset:1024 sc1
	global_store_dwordx4 v131, v[38:41], s[84:85] offset:2048 sc1
	global_store_dwordx4 v131, v[34:37], s[84:85] offset:3072 sc1
	v_add_u32_e32 v131, 0x1000, v131
	global_store_dwordx4 v131, v[30:33], s[84:85] offset:0 sc1
	global_store_dwordx4 v131, v[26:29], s[84:85] offset:1024 sc1
	global_store_dwordx4 v131, v[22:25], s[84:85] offset:2048 sc1
	global_store_dwordx4 v131, v[18:21], s[84:85] offset:3072 sc1
	v_add_u32_e32 v131, 0x1000, v131
	global_store_dwordx4 v131, v[14:17], s[84:85] offset:0 sc1
	global_store_dwordx4 v131, v[10:13], s[84:85] offset:1024 sc1
	global_store_dwordx4 v131, v[6:9], s[84:85] offset:2048 sc1
	global_store_dwordx4 v131, v[2:5], s[84:85] offset:3072 sc1
.Lsr0_nost:
	s_waitcnt vmcnt(0)
	s_barrier
	s_and_b32 s0, s21, 3
	s_lshl_b32 s0, s0, 6
	s_add_u32 s0, s0, 0x5a180c0
	v_mov_b32_e32 v132, s0
	v_mov_b32_e32 v133, 1
	s_or_b32 s1, s15, s14
	s_cmp_lg_u32 s1, 0
	s_cbranch_scc1 .Lsr0_spin
	s_mov_b64 exec, 1
	global_atomic_add v132, v133, s[84:85]
	s_mov_b64 exec, -1
.Lsr0_spin:
	s_mov_b32 s1, 0
.Lsr0_poll:
	global_load_dword v133, v132, s[84:85] sc1
	s_waitcnt vmcnt(0)
	v_readfirstlane_b32 s0, v133
	s_cmp_ge_u32 s0, 16
	s_cbranch_scc1 .Lsr0_go
	s_sleep 2
	s_add_i32 s1, s1, 1
	s_cmp_lt_u32 s1, 0x2000
	s_cbranch_scc1 .Lsr0_poll
.Lsr0_go:
	buffer_inv sc1
	s_sub_i32 s0, s21, 0x100
	s_lshr_b32 s0, s0, 2
	s_and_b32 s1, s21, 3
	s_lshl_b32 s1, s1, 17
	s_lshl_b32 vcc_lo, s0, 13
	s_add_i32 s1, s1, vcc_lo
	s_lshl_b32 vcc_lo, s15, 12
	s_add_i32 s1, s1, vcc_lo
	s_lshl_b32 vcc_lo, s14, 10
	s_add_i32 s1, s1, vcc_lo
	s_add_u32 s1, s1, 0xe219000
	v_add_u32_e32 v131, s1, v130
	global_load_dwordx4 v[2:5], v131, s[84:85] sc1
	v_add_u32_e32 v131, 0x80000, v131
	global_load_dwordx4 v[6:9], v131, s[84:85] sc1
	v_add_u32_e32 v131, 0x80000, v131
	global_load_dwordx4 v[10:13], v131, s[84:85] sc1
	v_add_u32_e32 v131, 0x80000, v131
	global_load_dwordx4 v[14:17], v131, s[84:85] sc1
	v_add_u32_e32 v131, 0x80000, v131
	global_load_dwordx4 v[18:21], v131, s[84:85] sc1
	v_add_u32_e32 v131, 0x80000, v131
	global_load_dwordx4 v[22:25], v131, s[84:85] sc1
	v_add_u32_e32 v131, 0x80000, v131
	global_load_dwordx4 v[26:29], v131, s[84:85] sc1
	v_add_u32_e32 v131, 0x80000, v131
	global_load_dwordx4 v[30:33], v131, s[84:85] sc1
	v_add_u32_e32 v131, 0x80000, v131
	global_load_dwordx4 v[34:37], v131, s[84:85] sc1
	v_add_u32_e32 v131, 0x80000, v131
	global_load_dwordx4 v[38:41], v131, s[84:85] sc1
	v_add_u32_e32 v131, 0x80000, v131
	global_load_dwordx4 v[42:45], v131, s[84:85] sc1
	v_add_u32_e32 v131, 0x80000, v131
	global_load_dwordx4 v[46:49], v131, s[84:85] sc1
	v_add_u32_e32 v131, 0x80000, v131
	global_load_dwordx4 v[50:53], v131, s[84:85] sc1
	v_add_u32_e32 v131, 0x80000, v131
	global_load_dwordx4 v[54:57], v131, s[84:85] sc1
	v_add_u32_e32 v131, 0x80000, v131
	global_load_dwordx4 v[58:61], v131, s[84:85] sc1
	v_add_u32_e32 v131, 0x80000, v131
	global_load_dwordx4 v[62:65], v131, s[84:85] sc1
	s_and_b32 s1, s0, 3
	s_lshl_b32 s1, s1, 1
	s_add_i32 s1, s1, s15
	s_lshl_b32 s1, s1, 4
	v_add_u32_e32 v134, s1, v167
	s_lshr_b32 s0, s0, 2
	s_lshl_b32 s0, s0, 6
	s_lshl_b32 vcc_lo, s14, 4
	s_add_i32 s0, s0, vcc_lo
	s_add_i32 s0, s0, s12
	s_lshl_b32 s0, s0, 2
	v_lshl_add_u32 v135, v166, 4, s0
	v_add_u32_e32 v136, 4, v134
	v_mul_lo_u32 v136, v136, s17
	v_add_u32_e32 v136, v136, v135
	v_add_u32_e32 v137, 0x4000, v134
	v_lshlrev_b32_e32 v137, 12, v137
	v_add_u32_e32 v137, v137, v135
	global_load_dwordx4 v[66:69], v136, s[6:7]
	global_load_dwordx4 v[70:73], v137, s[82:83]
	s_waitcnt vmcnt(16)
	v_add_f32_e32 v2, v2, v6
	v_add_f32_e32 v3, v3, v7
	v_add_f32_e32 v4, v4, v8
	v_add_f32_e32 v5, v5, v9
	s_waitcnt vmcnt(15)
	v_add_f32_e32 v2, v2, v10
	v_add_f32_e32 v3, v3, v11
	v_add_f32_e32 v4, v4, v12
	v_add_f32_e32 v5, v5, v13
	s_waitcnt vmcnt(14)
	v_add_f32_e32 v2, v2, v14
	v_add_f32_e32 v3, v3, v15
	v_add_f32_e32 v4, v4, v16
	v_add_f32_e32 v5, v5, v17
	s_waitcnt vmcnt(13)
	v_add_f32_e32 v2, v2, v18
	v_add_f32_e32 v3, v3, v19
	v_add_f32_e32 v4, v4, v20
	v_add_f32_e32 v5, v5, v21
	s_waitcnt vmcnt(12)
	v_add_f32_e32 v2, v2, v22
	v_add_f32_e32 v3, v3, v23
	v_add_f32_e32 v4, v4, v24
	v_add_f32_e32 v5, v5, v25
	s_waitcnt vmcnt(11)
	v_add_f32_e32 v2, v2, v26
	v_add_f32_e32 v3, v3, v27
	v_add_f32_e32 v4, v4, v28
	v_add_f32_e32 v5, v5, v29
	s_waitcnt vmcnt(10)
	v_add_f32_e32 v2, v2, v30
	v_add_f32_e32 v3, v3, v31
	v_add_f32_e32 v4, v4, v32
	v_add_f32_e32 v5, v5, v33
	s_waitcnt vmcnt(9)
	v_add_f32_e32 v2, v2, v34
	v_add_f32_e32 v3, v3, v35
	v_add_f32_e32 v4, v4, v36
	v_add_f32_e32 v5, v5, v37
	s_waitcnt vmcnt(8)
	v_add_f32_e32 v2, v2, v38
	v_add_f32_e32 v3, v3, v39
	v_add_f32_e32 v4, v4, v40
	v_add_f32_e32 v5, v5, v41
	s_waitcnt vmcnt(7)
	v_add_f32_e32 v2, v2, v42
	v_add_f32_e32 v3, v3, v43
	v_add_f32_e32 v4, v4, v44
	v_add_f32_e32 v5, v5, v45
	s_waitcnt vmcnt(6)
	v_add_f32_e32 v2, v2, v46
	v_add_f32_e32 v3, v3, v47
	v_add_f32_e32 v4, v4, v48
	v_add_f32_e32 v5, v5, v49
	s_waitcnt vmcnt(5)
	v_add_f32_e32 v2, v2, v50
	v_add_f32_e32 v3, v3, v51
	v_add_f32_e32 v4, v4, v52
	v_add_f32_e32 v5, v5, v53
	s_waitcnt vmcnt(4)
	v_add_f32_e32 v2, v2, v54
	v_add_f32_e32 v3, v3, v55
	v_add_f32_e32 v4, v4, v56
	v_add_f32_e32 v5, v5, v57
	s_waitcnt vmcnt(3)
	v_add_f32_e32 v2, v2, v58
	v_add_f32_e32 v3, v3, v59
	v_add_f32_e32 v4, v4, v60
	v_add_f32_e32 v5, v5, v61
	s_waitcnt vmcnt(2)
	v_add_f32_e32 v2, v2, v62
	v_add_f32_e32 v3, v3, v63
	v_add_f32_e32 v4, v4, v64
	v_add_f32_e32 v5, v5, v65
	s_waitcnt vmcnt(0)
	v_fmac_f32_e32 v70, v66, v2
	v_fmac_f32_e32 v71, v67, v3
	v_fmac_f32_e32 v72, v68, v4
	v_fmac_f32_e32 v73, v69, v5
	global_store_dwordx4 v137, v[70:73], s[82:83]
	s_mov_b64 s[10:11], exec
	s_branch .LBB0_1327

.Lop1_orig:
	s_sub_i32 s0, s21, 0x100
	s_lshl_b32 s0, s0, 17
	s_lshl_b32 s1, s14, 15
	s_add_i32 s0, s0, s1
	s_add_u32 s0, s0, 0xea19000
	v_lshl_add_u32 v130, v166, 4, v167
	v_lshlrev_b32_e32 v130, 4, v130
	v_add_u32_e32 v131, s0, v130
	s_cmp_lg_u32 s15, 0
	s_cbranch_scc1 .Lsr1_nost
	global_store_dwordx4 v131, v[126:129], s[84:85] offset:0 sc1
	global_store_dwordx4 v131, v[122:125], s[84:85] offset:1024 sc1
	global_store_dwordx4 v131, v[118:121], s[84:85] offset:2048 sc1
	global_store_dwordx4 v131, v[114:117], s[84:85] offset:3072 sc1
	v_add_u32_e32 v131, 0x1000, v131
	global_store_dwordx4 v131, v[110:113], s[84:85] offset:0 sc1
	global_store_dwordx4 v131, v[106:109], s[84:85] offset:1024 sc1
	global_store_dwordx4 v131, v[102:105], s[84:85] offset:2048 sc1
	global_store_dwordx4 v131, v[98:101], s[84:85] offset:3072 sc1
	v_add_u32_e32 v131, 0x1000, v131
	global_store_dwordx4 v131, v[94:97], s[84:85] offset:0 sc1
	global_store_dwordx4 v131, v[90:93], s[84:85] offset:1024 sc1
	global_store_dwordx4 v131, v[86:89], s[84:85] offset:2048 sc1
	global_store_dwordx4 v131, v[82:85], s[84:85] offset:3072 sc1
	v_add_u32_e32 v131, 0x1000, v131
	global_store_dwordx4 v131, v[78:81], s[84:85] offset:0 sc1
	global_store_dwordx4 v131, v[74:77], s[84:85] offset:1024 sc1
	global_store_dwordx4 v131, v[70:73], s[84:85] offset:2048 sc1
	global_store_dwordx4 v131, v[66:69], s[84:85] offset:3072 sc1
	v_add_u32_e32 v131, 0x1000, v131
	global_store_dwordx4 v131, v[62:65], s[84:85] offset:0 sc1
	global_store_dwordx4 v131, v[58:61], s[84:85] offset:1024 sc1
	global_store_dwordx4 v131, v[54:57], s[84:85] offset:2048 sc1
	global_store_dwordx4 v131, v[50:53], s[84:85] offset:3072 sc1
	v_add_u32_e32 v131, 0x1000, v131
	global_store_dwordx4 v131, v[46:49], s[84:85] offset:0 sc1
	global_store_dwordx4 v131, v[42:45], s[84:85] offset:1024 sc1
	global_store_dwordx4 v131, v[38:41], s[84:85] offset:2048 sc1
	global_store_dwordx4 v131, v[34:37], s[84:85] offset:3072 sc1
	v_add_u32_e32 v131, 0x1000, v131
	global_store_dwordx4 v131, v[30:33], s[84:85] offset:0 sc1
	global_store_dwordx4 v131, v[26:29], s[84:85] offset:1024 sc1
	global_store_dwordx4 v131, v[22:25], s[84:85] offset:2048 sc1
	global_store_dwordx4 v131, v[18:21], s[84:85] offset:3072 sc1
	v_add_u32_e32 v131, 0x1000, v131
	global_store_dwordx4 v131, v[14:17], s[84:85] offset:0 sc1
	global_store_dwordx4 v131, v[10:13], s[84:85] offset:1024 sc1
	global_store_dwordx4 v131, v[6:9], s[84:85] offset:2048 sc1
	global_store_dwordx4 v131, v[2:5], s[84:85] offset:3072 sc1
.Lsr1_nost:
	s_waitcnt vmcnt(0)
	s_barrier
	s_and_b32 s0, s21, 3
	s_lshl_b32 s0, s0, 6
	s_add_u32 s0, s0, 0x5a181c0
	v_mov_b32_e32 v132, s0
	v_mov_b32_e32 v133, 1
	s_or_b32 s1, s15, s14
	s_cmp_lg_u32 s1, 0
	s_cbranch_scc1 .Lsr1_spin
	s_mov_b64 exec, 1
	global_atomic_add v132, v133, s[84:85]
	s_mov_b64 exec, -1

.Lsr1_go:
	buffer_inv sc1
	s_sub_i32 s0, s21, 0x100
	s_lshr_b32 s0, s0, 2
	s_and_b32 s1, s21, 3
	s_lshl_b32 s1, s1, 17
	s_lshl_b32 vcc_lo, s0, 13
	s_add_i32 s1, s1, vcc_lo
	s_lshl_b32 vcc_lo, s15, 12
	s_add_i32 s1, s1, vcc_lo
	s_lshl_b32 vcc_lo, s14, 10
	s_add_i32 s1, s1, vcc_lo
	s_add_u32 s1, s1, 0xea19000
	v_add_u32_e32 v131, s1, v130
	global_load_dwordx4 v[2:5], v131, s[84:85] sc1
	v_add_u32_e32 v131, 0x80000, v131
	global_load_dwordx4 v[6:9], v131, s[84:85] sc1
	v_add_u32_e32 v131, 0x80000, v131
	global_load_dwordx4 v[10:13], v131, s[84:85] sc1
	v_add_u32_e32 v131, 0x80000, v131
	global_load_dwordx4 v[14:17], v131, s[84:85] sc1
	v_add_u32_e32 v131, 0x80000, v131
	global_load_dwordx4 v[18:21], v131, s[84:85] sc1
	v_add_u32_e32 v131, 0x80000, v131
	global_load_dwordx4 v[22:25], v131, s[84:85] sc1
	v_add_u32_e32 v131, 0x80000, v131
	global_load_dwordx4 v[26:29], v131, s[84:85] sc1
	v_add_u32_e32 v131, 0x80000, v131
	global_load_dwordx4 v[30:33], v131, s[84:85] sc1
	v_add_u32_e32 v131, 0x80000, v131
	global_load_dwordx4 v[34:37], v131, s[84:85] sc1
	v_add_u32_e32 v131, 0x80000, v131
	global_load_dwordx4 v[38:41], v131, s[84:85] sc1
	v_add_u32_e32 v131, 0x80000, v131
	global_load_dwordx4 v[42:45], v131, s[84:85] sc1
	v_add_u32_e32 v131, 0x80000, v131
	global_load_dwordx4 v[46:49], v131, s[84:85] sc1
	v_add_u32_e32 v131, 0x80000, v131
	global_load_dwordx4 v[50:53], v131, s[84:85] sc1
	v_add_u32_e32 v131, 0x80000, v131
	global_load_dwordx4 v[54:57], v131, s[84:85] sc1
	v_add_u32_e32 v131, 0x80000, v131
	global_load_dwordx4 v[58:61], v131, s[84:85] sc1
	v_add_u32_e32 v131, 0x80000, v131
	global_load_dwordx4 v[62:65], v131, s[84:85] sc1
	s_and_b32 s1, s0, 3
	s_lshl_b32 s1, s1, 1
	s_add_i32 s1, s1, s15
	s_lshl_b32 s1, s1, 4
	v_add_u32_e32 v134, s1, v167
	s_lshr_b32 s0, s0, 2
	s_lshl_b32 s0, s0, 6
	s_lshl_b32 vcc_lo, s14, 4
	s_add_i32 s0, s0, vcc_lo
	s_add_i32 s0, s0, s12
	s_lshl_b32 s0, s0, 2
	v_lshl_add_u32 v135, v166, 4, s0
	v_add_u32_e32 v136, 4, v134
	v_mul_lo_u32 v136, v136, s17
	v_add_u32_e32 v136, v136, v135
	v_add_u32_e32 v137, 0x4000, v134
	v_lshlrev_b32_e32 v137, 12, v137
	v_add_u32_e32 v137, v137, v135
	global_load_dwordx4 v[66:69], v136, s[4:5]
	global_load_dwordx4 v[70:73], v137, s[82:83]
	s_waitcnt vmcnt(16)
	v_add_f32_e32 v2, v2, v6
	v_add_f32_e32 v3, v3, v7
	v_add_f32_e32 v4, v4, v8
	v_add_f32_e32 v5, v5, v9
	s_waitcnt vmcnt(15)
	v_add_f32_e32 v2, v2, v10
	v_add_f32_e32 v3, v3, v11
	v_add_f32_e32 v4, v4, v12
	v_add_f32_e32 v5, v5, v13
	s_waitcnt vmcnt(14)
	v_add_f32_e32 v2, v2, v14
	v_add_f32_e32 v3, v3, v15
	v_add_f32_e32 v4, v4, v16
	v_add_f32_e32 v5, v5, v17
	s_waitcnt vmcnt(13)
	v_add_f32_e32 v2, v2, v18
	v_add_f32_e32 v3, v3, v19
	v_add_f32_e32 v4, v4, v20
	v_add_f32_e32 v5, v5, v21
	s_waitcnt vmcnt(12)
	v_add_f32_e32 v2, v2, v22
	v_add_f32_e32 v3, v3, v23
	v_add_f32_e32 v4, v4, v24
	v_add_f32_e32 v5, v5, v25
	s_waitcnt vmcnt(11)
	v_add_f32_e32 v2, v2, v26
	v_add_f32_e32 v3, v3, v27
	v_add_f32_e32 v4, v4, v28
	v_add_f32_e32 v5, v5, v29
	s_waitcnt vmcnt(10)
	v_add_f32_e32 v2, v2, v30
	v_add_f32_e32 v3, v3, v31
	v_add_f32_e32 v4, v4, v32
	v_add_f32_e32 v5, v5, v33
	s_waitcnt vmcnt(9)
	v_add_f32_e32 v2, v2, v34
	v_add_f32_e32 v3, v3, v35
	v_add_f32_e32 v4, v4, v36
	v_add_f32_e32 v5, v5, v37
	s_waitcnt vmcnt(8)
	v_add_f32_e32 v2, v2, v38
	v_add_f32_e32 v3, v3, v39
	v_add_f32_e32 v4, v4, v40
	v_add_f32_e32 v5, v5, v41
	s_waitcnt vmcnt(7)
	v_add_f32_e32 v2, v2, v42
	v_add_f32_e32 v3, v3, v43
	v_add_f32_e32 v4, v4, v44
	v_add_f32_e32 v5, v5, v45
	s_waitcnt vmcnt(6)
	v_add_f32_e32 v2, v2, v46
	v_add_f32_e32 v3, v3, v47
	v_add_f32_e32 v4, v4, v48
	v_add_f32_e32 v5, v5, v49
	s_waitcnt vmcnt(5)
	v_add_f32_e32 v2, v2, v50
	v_add_f32_e32 v3, v3, v51
	v_add_f32_e32 v4, v4, v52
	v_add_f32_e32 v5, v5, v53
	s_waitcnt vmcnt(4)
	v_add_f32_e32 v2, v2, v54
	v_add_f32_e32 v3, v3, v55
	v_add_f32_e32 v4, v4, v56
	v_add_f32_e32 v5, v5, v57
	s_waitcnt vmcnt(3)
	v_add_f32_e32 v2, v2, v58
	v_add_f32_e32 v3, v3, v59
	v_add_f32_e32 v4, v4, v60
	v_add_f32_e32 v5, v5, v61
	s_waitcnt vmcnt(2)
	v_add_f32_e32 v2, v2, v62
	v_add_f32_e32 v3, v3, v63
	v_add_f32_e32 v4, v4, v64
	v_add_f32_e32 v5, v5, v65
	s_waitcnt vmcnt(0)
	v_fmac_f32_e32 v70, v66, v2
	v_fmac_f32_e32 v71, v67, v3
	v_fmac_f32_e32 v72, v68, v4
	v_fmac_f32_e32 v73, v69, v5
	global_store_dwordx4 v137, v[70:73], s[82:83]
	s_mov_b64 s[10:11], exec
	s_branch .LBB0_1660

.Lop2_orig:
	s_sub_i32 s0, s19, 0x100
	s_lshl_b32 s0, s0, 17
	s_lshl_b32 s1, s12, 15
	s_add_i32 s0, s0, s1
	s_add_u32 s0, s0, 0xf219000
	v_lshl_add_u32 v130, v166, 4, v167
	v_lshlrev_b32_e32 v130, 4, v130
	v_add_u32_e32 v131, s0, v130
	s_cmp_lg_u32 s13, 0
	s_cbranch_scc1 .Lsr2_nost
	global_store_dwordx4 v131, v[126:129], s[84:85] offset:0 sc1
	global_store_dwordx4 v131, v[122:125], s[84:85] offset:1024 sc1
	global_store_dwordx4 v131, v[118:121], s[84:85] offset:2048 sc1
	global_store_dwordx4 v131, v[114:117], s[84:85] offset:3072 sc1
	v_add_u32_e32 v131, 0x1000, v131
	global_store_dwordx4 v131, v[110:113], s[84:85] offset:0 sc1
	global_store_dwordx4 v131, v[106:109], s[84:85] offset:1024 sc1
	global_store_dwordx4 v131, v[102:105], s[84:85] offset:2048 sc1
	global_store_dwordx4 v131, v[98:101], s[84:85] offset:3072 sc1
	v_add_u32_e32 v131, 0x1000, v131
	global_store_dwordx4 v131, v[94:97], s[84:85] offset:0 sc1
	global_store_dwordx4 v131, v[90:93], s[84:85] offset:1024 sc1
	global_store_dwordx4 v131, v[86:89], s[84:85] offset:2048 sc1
	global_store_dwordx4 v131, v[82:85], s[84:85] offset:3072 sc1
	v_add_u32_e32 v131, 0x1000, v131
	global_store_dwordx4 v131, v[78:81], s[84:85] offset:0 sc1
	global_store_dwordx4 v131, v[74:77], s[84:85] offset:1024 sc1
	global_store_dwordx4 v131, v[70:73], s[84:85] offset:2048 sc1
	global_store_dwordx4 v131, v[66:69], s[84:85] offset:3072 sc1
	v_add_u32_e32 v131, 0x1000, v131
	global_store_dwordx4 v131, v[62:65], s[84:85] offset:0 sc1
	global_store_dwordx4 v131, v[58:61], s[84:85] offset:1024 sc1
	global_store_dwordx4 v131, v[54:57], s[84:85] offset:2048 sc1
	global_store_dwordx4 v131, v[50:53], s[84:85] offset:3072 sc1
	v_add_u32_e32 v131, 0x1000, v131
	global_store_dwordx4 v131, v[46:49], s[84:85] offset:0 sc1
	global_store_dwordx4 v131, v[42:45], s[84:85] offset:1024 sc1
	global_store_dwordx4 v131, v[38:41], s[84:85] offset:2048 sc1
	global_store_dwordx4 v131, v[34:37], s[84:85] offset:3072 sc1
	v_add_u32_e32 v131, 0x1000, v131
	global_store_dwordx4 v131, v[30:33], s[84:85] offset:0 sc1
	global_store_dwordx4 v131, v[26:29], s[84:85] offset:1024 sc1
	global_store_dwordx4 v131, v[22:25], s[84:85] offset:2048 sc1
	global_store_dwordx4 v131, v[18:21], s[84:85] offset:3072 sc1
	v_add_u32_e32 v131, 0x1000, v131
	global_store_dwordx4 v131, v[14:17], s[84:85] offset:0 sc1
	global_store_dwordx4 v131, v[10:13], s[84:85] offset:1024 sc1
	global_store_dwordx4 v131, v[6:9], s[84:85] offset:2048 sc1
	global_store_dwordx4 v131, v[2:5], s[84:85] offset:3072 sc1
.Lsr2_nost:
	s_waitcnt vmcnt(0)
	s_barrier
	s_and_b32 s0, s19, 3
	s_lshl_b32 s0, s0, 6
	s_add_u32 s0, s0, 0x5a182c0
	v_mov_b32_e32 v132, s0
	v_mov_b32_e32 v133, 1
	s_or_b32 s1, s13, s12
	s_cmp_lg_u32 s1, 0
	s_cbranch_scc1 .Lsr2_spin
	s_mov_b64 exec, 1
	global_atomic_add v132, v133, s[84:85]
	s_mov_b64 exec, -1

.Lsr2_go:
	buffer_inv sc1
	s_sub_i32 s0, s19, 0x100
	s_lshr_b32 s0, s0, 2
	s_and_b32 s1, s19, 3
	s_lshl_b32 s1, s1, 17
	s_lshl_b32 vcc_lo, s0, 13
	s_add_i32 s1, s1, vcc_lo
	s_lshl_b32 vcc_lo, s13, 12
	s_add_i32 s1, s1, vcc_lo
	s_lshl_b32 vcc_lo, s12, 10
	s_add_i32 s1, s1, vcc_lo
	s_add_u32 s1, s1, 0xf219000
	v_add_u32_e32 v131, s1, v130
	global_load_dwordx4 v[2:5], v131, s[84:85] sc1
	v_add_u32_e32 v131, 0x80000, v131
	global_load_dwordx4 v[6:9], v131, s[84:85] sc1
	v_add_u32_e32 v131, 0x80000, v131
	global_load_dwordx4 v[10:13], v131, s[84:85] sc1
	v_add_u32_e32 v131, 0x80000, v131
	global_load_dwordx4 v[14:17], v131, s[84:85] sc1
	v_add_u32_e32 v131, 0x80000, v131
	global_load_dwordx4 v[18:21], v131, s[84:85] sc1
	v_add_u32_e32 v131, 0x80000, v131
	global_load_dwordx4 v[22:25], v131, s[84:85] sc1
	v_add_u32_e32 v131, 0x80000, v131
	global_load_dwordx4 v[26:29], v131, s[84:85] sc1
	v_add_u32_e32 v131, 0x80000, v131
	global_load_dwordx4 v[30:33], v131, s[84:85] sc1
	v_add_u32_e32 v131, 0x80000, v131
	global_load_dwordx4 v[34:37], v131, s[84:85] sc1
	v_add_u32_e32 v131, 0x80000, v131
	global_load_dwordx4 v[38:41], v131, s[84:85] sc1
	v_add_u32_e32 v131, 0x80000, v131
	global_load_dwordx4 v[42:45], v131, s[84:85] sc1
	v_add_u32_e32 v131, 0x80000, v131
	global_load_dwordx4 v[46:49], v131, s[84:85] sc1
	v_add_u32_e32 v131, 0x80000, v131
	global_load_dwordx4 v[50:53], v131, s[84:85] sc1
	v_add_u32_e32 v131, 0x80000, v131
	global_load_dwordx4 v[54:57], v131, s[84:85] sc1
	v_add_u32_e32 v131, 0x80000, v131
	global_load_dwordx4 v[58:61], v131, s[84:85] sc1
	v_add_u32_e32 v131, 0x80000, v131
	global_load_dwordx4 v[62:65], v131, s[84:85] sc1
	s_and_b32 s1, s0, 3
	s_lshl_b32 s1, s1, 1
	s_add_i32 s1, s1, s13
	s_lshl_b32 s1, s1, 4
	v_add_u32_e32 v134, s1, v167
	s_lshr_b32 s0, s0, 2
	s_lshl_b32 s0, s0, 6
	s_lshl_b32 vcc_lo, s12, 4
	s_add_i32 s0, s0, vcc_lo
	s_add_i32 s0, s0, s10
	s_lshl_b32 s0, s0, 2
	v_lshl_add_u32 v135, v166, 4, s0
	v_add_u32_e32 v136, 136, v134
	v_mul_lo_u32 v136, v136, s15
	v_add_u32_e32 v136, v136, v135
	v_add_u32_e32 v137, 0x4000, v134
	v_lshlrev_b32_e32 v137, 12, v137
	v_add_u32_e32 v137, v137, v135
	global_load_dwordx4 v[66:69], v136, s[4:5]
	global_load_dwordx4 v[70:73], v137, s[82:83]
	s_waitcnt vmcnt(16)
	v_add_f32_e32 v2, v2, v6
	v_add_f32_e32 v3, v3, v7
	v_add_f32_e32 v4, v4, v8
	v_add_f32_e32 v5, v5, v9
	s_waitcnt vmcnt(15)
	v_add_f32_e32 v2, v2, v10
	v_add_f32_e32 v3, v3, v11
	v_add_f32_e32 v4, v4, v12
	v_add_f32_e32 v5, v5, v13
	s_waitcnt vmcnt(14)
	v_add_f32_e32 v2, v2, v14
	v_add_f32_e32 v3, v3, v15
	v_add_f32_e32 v4, v4, v16
	v_add_f32_e32 v5, v5, v17
	s_waitcnt vmcnt(13)
	v_add_f32_e32 v2, v2, v18
	v_add_f32_e32 v3, v3, v19
	v_add_f32_e32 v4, v4, v20
	v_add_f32_e32 v5, v5, v21
	s_waitcnt vmcnt(12)
	v_add_f32_e32 v2, v2, v22
	v_add_f32_e32 v3, v3, v23
	v_add_f32_e32 v4, v4, v24
	v_add_f32_e32 v5, v5, v25
	s_waitcnt vmcnt(11)
	v_add_f32_e32 v2, v2, v26
	v_add_f32_e32 v3, v3, v27
	v_add_f32_e32 v4, v4, v28
	v_add_f32_e32 v5, v5, v29
	s_waitcnt vmcnt(10)
	v_add_f32_e32 v2, v2, v30
	v_add_f32_e32 v3, v3, v31
	v_add_f32_e32 v4, v4, v32
	v_add_f32_e32 v5, v5, v33
	s_waitcnt vmcnt(9)
	v_add_f32_e32 v2, v2, v34
	v_add_f32_e32 v3, v3, v35
	v_add_f32_e32 v4, v4, v36
	v_add_f32_e32 v5, v5, v37
	s_waitcnt vmcnt(8)
	v_add_f32_e32 v2, v2, v38
	v_add_f32_e32 v3, v3, v39
	v_add_f32_e32 v4, v4, v40
	v_add_f32_e32 v5, v5, v41
	s_waitcnt vmcnt(7)
	v_add_f32_e32 v2, v2, v42
	v_add_f32_e32 v3, v3, v43
	v_add_f32_e32 v4, v4, v44
	v_add_f32_e32 v5, v5, v45
	s_waitcnt vmcnt(6)
	v_add_f32_e32 v2, v2, v46
	v_add_f32_e32 v3, v3, v47
	v_add_f32_e32 v4, v4, v48
	v_add_f32_e32 v5, v5, v49
	s_waitcnt vmcnt(5)
	v_add_f32_e32 v2, v2, v50
	v_add_f32_e32 v3, v3, v51
	v_add_f32_e32 v4, v4, v52
	v_add_f32_e32 v5, v5, v53
	s_waitcnt vmcnt(4)
	v_add_f32_e32 v2, v2, v54
	v_add_f32_e32 v3, v3, v55
	v_add_f32_e32 v4, v4, v56
	v_add_f32_e32 v5, v5, v57
	s_waitcnt vmcnt(3)
	v_add_f32_e32 v2, v2, v58
	v_add_f32_e32 v3, v3, v59
	v_add_f32_e32 v4, v4, v60
	v_add_f32_e32 v5, v5, v61
	s_waitcnt vmcnt(2)
	v_add_f32_e32 v2, v2, v62
	v_add_f32_e32 v3, v3, v63
	v_add_f32_e32 v4, v4, v64
	v_add_f32_e32 v5, v5, v65
	s_waitcnt vmcnt(0)
	v_fmac_f32_e32 v70, v66, v2
	v_fmac_f32_e32 v71, v67, v3
	v_fmac_f32_e32 v72, v68, v4
	v_fmac_f32_e32 v73, v69, v5
	global_store_dwordx4 v137, v[70:73], s[82:83]
	s_mov_b64 s[8:9], exec
	s_branch .LBB0_2752

.Lop3_orig:
	s_sub_i32 s0, s2, 0x100
	s_lshl_b32 s0, s0, 17
	s_lshl_b32 s1, s14, 15
	s_add_i32 s0, s0, s1
	s_add_u32 s0, s0, 0xfa19000
	v_lshl_add_u32 v130, v166, 4, v167
	v_lshlrev_b32_e32 v130, 4, v130
	v_add_u32_e32 v131, s0, v130
	s_cmp_lg_u32 s15, 0
	s_cbranch_scc1 .Lsr3_nost
	global_store_dwordx4 v131, v[126:129], s[84:85] offset:0 sc1
	global_store_dwordx4 v131, v[122:125], s[84:85] offset:1024 sc1
	global_store_dwordx4 v131, v[118:121], s[84:85] offset:2048 sc1
	global_store_dwordx4 v131, v[114:117], s[84:85] offset:3072 sc1
	v_add_u32_e32 v131, 0x1000, v131
	global_store_dwordx4 v131, v[110:113], s[84:85] offset:0 sc1
	global_store_dwordx4 v131, v[106:109], s[84:85] offset:1024 sc1
	global_store_dwordx4 v131, v[102:105], s[84:85] offset:2048 sc1
	global_store_dwordx4 v131, v[98:101], s[84:85] offset:3072 sc1
	v_add_u32_e32 v131, 0x1000, v131
	global_store_dwordx4 v131, v[94:97], s[84:85] offset:0 sc1
	global_store_dwordx4 v131, v[90:93], s[84:85] offset:1024 sc1
	global_store_dwordx4 v131, v[86:89], s[84:85] offset:2048 sc1
	global_store_dwordx4 v131, v[82:85], s[84:85] offset:3072 sc1
	v_add_u32_e32 v131, 0x1000, v131
	global_store_dwordx4 v131, v[78:81], s[84:85] offset:0 sc1
	global_store_dwordx4 v131, v[74:77], s[84:85] offset:1024 sc1
	global_store_dwordx4 v131, v[70:73], s[84:85] offset:2048 sc1
	global_store_dwordx4 v131, v[66:69], s[84:85] offset:3072 sc1
	v_add_u32_e32 v131, 0x1000, v131
	global_store_dwordx4 v131, v[62:65], s[84:85] offset:0 sc1
	global_store_dwordx4 v131, v[58:61], s[84:85] offset:1024 sc1
	global_store_dwordx4 v131, v[54:57], s[84:85] offset:2048 sc1
	global_store_dwordx4 v131, v[50:53], s[84:85] offset:3072 sc1
	v_add_u32_e32 v131, 0x1000, v131
	global_store_dwordx4 v131, v[46:49], s[84:85] offset:0 sc1
	global_store_dwordx4 v131, v[42:45], s[84:85] offset:1024 sc1
	global_store_dwordx4 v131, v[38:41], s[84:85] offset:2048 sc1
	global_store_dwordx4 v131, v[34:37], s[84:85] offset:3072 sc1
	v_add_u32_e32 v131, 0x1000, v131
	global_store_dwordx4 v131, v[30:33], s[84:85] offset:0 sc1
	global_store_dwordx4 v131, v[26:29], s[84:85] offset:1024 sc1
	global_store_dwordx4 v131, v[22:25], s[84:85] offset:2048 sc1
	global_store_dwordx4 v131, v[18:21], s[84:85] offset:3072 sc1
	v_add_u32_e32 v131, 0x1000, v131
	global_store_dwordx4 v131, v[14:17], s[84:85] offset:0 sc1
	global_store_dwordx4 v131, v[10:13], s[84:85] offset:1024 sc1
	global_store_dwordx4 v131, v[6:9], s[84:85] offset:2048 sc1
	global_store_dwordx4 v131, v[2:5], s[84:85] offset:3072 sc1
.Lsr3_nost:
	s_waitcnt vmcnt(0)
	s_barrier
	s_and_b32 s0, s2, 3
	s_lshl_b32 s0, s0, 6
	s_add_u32 s0, s0, 0x5a183c0
	v_mov_b32_e32 v132, s0
	v_mov_b32_e32 v133, 1
	s_or_b32 s1, s15, s14
	s_cmp_lg_u32 s1, 0
	s_cbranch_scc1 .Lsr3_spin
	s_mov_b64 exec, 1
	global_atomic_add v132, v133, s[84:85]
	s_mov_b64 exec, -1

.Lsr3_go:
	buffer_inv sc1
	s_sub_i32 s0, s2, 0x100
	s_lshr_b32 s0, s0, 2
	s_and_b32 s1, s2, 3
	s_lshl_b32 s1, s1, 17
	s_lshl_b32 vcc_lo, s0, 13
	s_add_i32 s1, s1, vcc_lo
	s_lshl_b32 vcc_lo, s15, 12
	s_add_i32 s1, s1, vcc_lo
	s_lshl_b32 vcc_lo, s14, 10
	s_add_i32 s1, s1, vcc_lo
	s_add_u32 s1, s1, 0xfa19000
	v_add_u32_e32 v131, s1, v130
	global_load_dwordx4 v[2:5], v131, s[84:85] sc1
	v_add_u32_e32 v131, 0x80000, v131
	global_load_dwordx4 v[6:9], v131, s[84:85] sc1
	v_add_u32_e32 v131, 0x80000, v131
	global_load_dwordx4 v[10:13], v131, s[84:85] sc1
	v_add_u32_e32 v131, 0x80000, v131
	global_load_dwordx4 v[14:17], v131, s[84:85] sc1
	v_add_u32_e32 v131, 0x80000, v131
	global_load_dwordx4 v[18:21], v131, s[84:85] sc1
	v_add_u32_e32 v131, 0x80000, v131
	global_load_dwordx4 v[22:25], v131, s[84:85] sc1
	v_add_u32_e32 v131, 0x80000, v131
	global_load_dwordx4 v[26:29], v131, s[84:85] sc1
	v_add_u32_e32 v131, 0x80000, v131
	global_load_dwordx4 v[30:33], v131, s[84:85] sc1
	v_add_u32_e32 v131, 0x80000, v131
	global_load_dwordx4 v[34:37], v131, s[84:85] sc1
	v_add_u32_e32 v131, 0x80000, v131
	global_load_dwordx4 v[38:41], v131, s[84:85] sc1
	v_add_u32_e32 v131, 0x80000, v131
	global_load_dwordx4 v[42:45], v131, s[84:85] sc1
	v_add_u32_e32 v131, 0x80000, v131
	global_load_dwordx4 v[46:49], v131, s[84:85] sc1
	v_add_u32_e32 v131, 0x80000, v131
	global_load_dwordx4 v[50:53], v131, s[84:85] sc1
	v_add_u32_e32 v131, 0x80000, v131
	global_load_dwordx4 v[54:57], v131, s[84:85] sc1
	v_add_u32_e32 v131, 0x80000, v131
	global_load_dwordx4 v[58:61], v131, s[84:85] sc1
	v_add_u32_e32 v131, 0x80000, v131
	global_load_dwordx4 v[62:65], v131, s[84:85] sc1
	s_and_b32 s1, s0, 3
	s_lshl_b32 s1, s1, 1
	s_add_i32 s1, s1, s15
	s_lshl_b32 s1, s1, 4
	v_add_u32_e32 v134, s1, v167
	s_lshr_b32 s0, s0, 2
	s_lshl_b32 s0, s0, 6
	s_lshl_b32 vcc_lo, s14, 4
	s_add_i32 s0, s0, vcc_lo
	s_add_i32 s0, s0, s12
	s_lshl_b32 s0, s0, 2
	v_lshl_add_u32 v135, v166, 4, s0
	v_add_u32_e32 v136, 136, v134
	v_mul_lo_u32 v136, v136, s17
	v_add_u32_e32 v136, v136, v135
	v_add_u32_e32 v137, 0x4000, v134
	v_lshlrev_b32_e32 v137, 12, v137
	v_add_u32_e32 v137, v137, v135
	global_load_dwordx4 v[66:69], v136, s[4:5]
	global_load_dwordx4 v[70:73], v137, s[82:83]
	s_waitcnt vmcnt(16)
	v_add_f32_e32 v2, v2, v6
	v_add_f32_e32 v3, v3, v7
	v_add_f32_e32 v4, v4, v8
	v_add_f32_e32 v5, v5, v9
	s_waitcnt vmcnt(15)
	v_add_f32_e32 v2, v2, v10
	v_add_f32_e32 v3, v3, v11
	v_add_f32_e32 v4, v4, v12
	v_add_f32_e32 v5, v5, v13
	s_waitcnt vmcnt(14)
	v_add_f32_e32 v2, v2, v14
	v_add_f32_e32 v3, v3, v15
	v_add_f32_e32 v4, v4, v16
	v_add_f32_e32 v5, v5, v17
	s_waitcnt vmcnt(13)
	v_add_f32_e32 v2, v2, v18
	v_add_f32_e32 v3, v3, v19
	v_add_f32_e32 v4, v4, v20
	v_add_f32_e32 v5, v5, v21
	s_waitcnt vmcnt(12)
	v_add_f32_e32 v2, v2, v22
	v_add_f32_e32 v3, v3, v23
	v_add_f32_e32 v4, v4, v24
	v_add_f32_e32 v5, v5, v25
	s_waitcnt vmcnt(11)
	v_add_f32_e32 v2, v2, v26
	v_add_f32_e32 v3, v3, v27
	v_add_f32_e32 v4, v4, v28
	v_add_f32_e32 v5, v5, v29
	s_waitcnt vmcnt(10)
	v_add_f32_e32 v2, v2, v30
	v_add_f32_e32 v3, v3, v31
	v_add_f32_e32 v4, v4, v32
	v_add_f32_e32 v5, v5, v33
	s_waitcnt vmcnt(9)
	v_add_f32_e32 v2, v2, v34
	v_add_f32_e32 v3, v3, v35
	v_add_f32_e32 v4, v4, v36
	v_add_f32_e32 v5, v5, v37
	s_waitcnt vmcnt(8)
	v_add_f32_e32 v2, v2, v38
	v_add_f32_e32 v3, v3, v39
	v_add_f32_e32 v4, v4, v40
	v_add_f32_e32 v5, v5, v41
	s_waitcnt vmcnt(7)
	v_add_f32_e32 v2, v2, v42
	v_add_f32_e32 v3, v3, v43
	v_add_f32_e32 v4, v4, v44
	v_add_f32_e32 v5, v5, v45
	s_waitcnt vmcnt(6)
	v_add_f32_e32 v2, v2, v46
	v_add_f32_e32 v3, v3, v47
	v_add_f32_e32 v4, v4, v48
	v_add_f32_e32 v5, v5, v49
	s_waitcnt vmcnt(5)
	v_add_f32_e32 v2, v2, v50
	v_add_f32_e32 v3, v3, v51
	v_add_f32_e32 v4, v4, v52
	v_add_f32_e32 v5, v5, v53
	s_waitcnt vmcnt(4)
	v_add_f32_e32 v2, v2, v54
	v_add_f32_e32 v3, v3, v55
	v_add_f32_e32 v4, v4, v56
	v_add_f32_e32 v5, v5, v57
	s_waitcnt vmcnt(3)
	v_add_f32_e32 v2, v2, v58
	v_add_f32_e32 v3, v3, v59
	v_add_f32_e32 v4, v4, v60
	v_add_f32_e32 v5, v5, v61
	s_waitcnt vmcnt(2)
	v_add_f32_e32 v2, v2, v62
	v_add_f32_e32 v3, v3, v63
	v_add_f32_e32 v4, v4, v64
	v_add_f32_e32 v5, v5, v65
	s_waitcnt vmcnt(0)
	v_fmac_f32_e32 v70, v66, v2
	v_fmac_f32_e32 v71, v67, v3
	v_fmac_f32_e32 v72, v68, v4
	v_fmac_f32_e32 v73, v69, v5
	global_store_dwordx4 v137, v[70:73], s[82:83]
	s_mov_b64 s[10:11], exec
	s_branch .LBB0_3085
